# speedup vs baseline: 1.0634x; 1.0376x over previous
; __device__ __forceinline__ void phase_ret_passC(const Params& p, char* smem) {
;     ...
;     store_tile(scr, 128, Cs, [&](float v, int n, int m) { return (n >= m) ? v * __builtin_amdgcn_exp2f((float)(n - m) * l2g) : 0.f; });
;     __threadfence();
;     __syncthreads();
;     const int c16 = tid & 15, rgrp = tid >> 4;
;     float ssp[8];
; #pragma unroll
;     for (int it = 0; it < 8; ++it) ssp[it] = 0.f;
; #pragma unroll 1
;     for (int eh = 0; eh < 2; ++eh) {
;       gemm_core<false, false>(QR + tok0 * 1024 + hh * 256, 1024, ST + ((long)((bh * 32 + c) * 256 + eh * 128)) * 256, 256, 256, smem, acc);
;       int nb = wp * 64 + g * 4 + 1;
;       asm volatile("" : "+v"(nb));
.LBB0_1689:
	s_or_b64 exec, exec, s[90:91]
	v_add_u32_e32 v17, v4, v21
	v_cvt_f32_i32_e32 v17, v17
	v_sub_u32_e32 v21, v4, v13
	v_cvt_f32_i32_e32 v21, v21
	v_sub_u32_e32 v20, v4, v12
	v_mul_f32_e32 v17, v109, v17
	v_exp_f32_e32 v17, v17
	v_cvt_f32_i32_e32 v20, v20
	v_sub_u32_e32 v23, v4, v9
	v_cvt_f32_i32_e32 v23, v23
	s_waitcnt lgkmcnt(2)
	v_mul_f32_e32 v24, v17, v16
	v_mul_f32_e32 v16, v109, v21
	v_sub_u32_e32 v17, v4, v10
	v_sub_u32_e32 v21, v4, v11
	v_cvt_f32_i32_e32 v17, v17
	v_cvt_f32_i32_e32 v22, v21
	v_mul_f32_e32 v20, v109, v20
	v_exp_f32_e32 v21, v16
	v_mul_f32_e32 v16, v109, v17
	v_mul_f32_e32 v17, v109, v22
	v_sub_u32_e32 v22, v4, v8
	v_exp_f32_e32 v20, v20
	v_cvt_f32_i32_e32 v22, v22
	v_exp_f32_e32 v16, v16
	v_exp_f32_e32 v17, v17
	v_mul_f32_e32 v23, v109, v23
	v_mul_f32_e32 v22, v109, v22
	v_cmp_gt_i32_e32 vcc, v4, v19
	s_waitcnt lgkmcnt(0)
	v_pk_mul_f32 v[20:21], v[20:21], v[0:1]
	v_exp_f32_e32 v22, v22
	v_exp_f32_e32 v23, v23
	v_cndmask_b32_e32 v19, 0, v24, vcc
	v_cvt_pk_bf16_f32 v1, v20, v21
	v_cmp_ge_i32_e32 vcc, v4, v12
	v_pk_mul_f32 v[2:3], v[16:17], v[2:3]
	v_cvt_pk_bf16_f32 v0, v5, v19
	v_cndmask_b32_e32 v5, 0, v1, vcc
	v_lshrrev_b32_e32 v1, 16, v1
	v_cmp_ge_i32_e32 vcc, v4, v13
	v_cvt_pk_bf16_f32 v2, v2, v3
	v_pk_mul_f32 v[14:15], v[22:23], v[14:15]
	v_cndmask_b32_e32 v1, 0, v1, vcc
	v_cmp_ge_i32_e32 vcc, v4, v10
	v_perm_b32 v1, v1, v5, s94
	s_lshl_b32 s1, s95, 8
	v_cndmask_b32_e32 v3, 0, v2, vcc
	v_lshrrev_b32_e32 v2, 16, v2
	v_cmp_ge_i32_e32 vcc, v4, v11
	s_lshl_b32 s2, s4, 1
	s_add_u32 s4, s26, s2
	v_cndmask_b32_e32 v2, 0, v2, vcc
	v_perm_b32 v2, v2, v3, s94
	v_cvt_pk_bf16_f32 v3, v14, v15
	v_cmp_ge_i32_e32 vcc, v4, v8
	s_addc_u32 s5, s27, 0
	s_lshl_b32 s34, s14, 8
	v_cndmask_b32_e32 v5, 0, v3, vcc
	v_lshrrev_b32_e32 v3, 16, v3
	v_cmp_ge_i32_e32 vcc, v4, v9
	s_lshl_b32 s2, s0, 1
	s_add_u32 s84, s22, s2
	v_cndmask_b32_e32 v3, 0, v3, vcc
	v_perm_b32 v3, v3, v5, s94
	v_ashrrev_i32_e32 v5, 31, v4
	v_lshlrev_b64 v[4:5], 8, v[4:5]
	v_lshl_add_u64 v[4:5], v[6:7], 0, v[4:5]
	global_store_dwordx4 v[4:5], v[0:3], off
	s_addc_u32 s85, s23, 0
	s_mov_b32 s14, 0
	v_ashrrev_i32_e32 v1, 1, v18
	v_lshrrev_b32_e32 v2, 2, v18
	v_ashrrev_i32_e32 v0, 4, v18
	v_and_b32_e32 v1, 0xffffffc0, v1
	v_and_b32_e32 v2, 12, v2
	v_or3_b32 v111, v2, v1, 1
	v_add_u32_e32 v2, 16, v0
	v_ashrrev_i32_e32 v3, 31, v2
	v_lshl_add_u64 v[70:71], s[8:9], 0, v[2:3]
	v_add_u32_e32 v2, 32, v0
	v_ashrrev_i32_e32 v3, 31, v2
	v_lshl_add_u64 v[72:73], s[8:9], 0, v[2:3]
	v_add_u32_e32 v2, 48, v0
	v_ashrrev_i32_e32 v3, 31, v2
	v_lshl_add_u64 v[74:75], s[8:9], 0, v[2:3]
	v_add_u32_e32 v2, 64, v0
	v_ashrrev_i32_e32 v3, 31, v2
	v_lshlrev_b32_e32 v1, 3, v18
	v_lshl_add_u64 v[76:77], s[8:9], 0, v[2:3]
	v_add_u32_e32 v2, 0x50, v0
	v_and_b32_e32 v110, 0x78, v1
	v_ashrrev_i32_e32 v1, 31, v0
	v_ashrrev_i32_e32 v3, 31, v2
	v_mul_lo_u32 v5, v0, s93
	v_lshl_add_u64 v[68:69], s[8:9], 0, v[0:1]
	v_lshl_add_u64 v[78:79], s[8:9], 0, v[2:3]
	v_add_u32_e32 v2, 0x60, v0
	v_add_u32_e32 v0, 0x70, v0
	v_ashrrev_i32_e32 v3, 31, v2
	v_ashrrev_i32_e32 v1, 31, v0
	v_lshl_add_u32 v4, v110, 2, 0
	v_lshlrev_b32_e32 v64, 1, v110
	v_lshl_add_u64 v[80:81], s[8:9], 0, v[2:3]
	v_lshl_add_u64 v[82:83], s[8:9], 0, v[0:1]
	v_lshl_add_u64 v[88:89], s[84:85], 0, v[64:65]
	v_lshlrev_b64 v[90:91], 11, v[68:69]
	v_lshlrev_b64 v[92:93], 11, v[70:71]
	v_lshlrev_b64 v[94:95], 11, v[72:73]
	v_lshlrev_b64 v[96:97], 11, v[74:75]
	v_lshlrev_b64 v[98:99], 11, v[76:77]
	v_lshlrev_b64 v[100:101], 11, v[78:79]
	v_lshlrev_b64 v[102:103], 11, v[80:81]
	v_lshlrev_b64 v[104:105], 11, v[82:83]
	s_mov_b64 s[8:9], -1
	v_add_u32_e32 v112, v4, v5
	v_mov_b32_e32 v67, v66
	v_mov_b32_e32 v84, v66
	v_mov_b32_e32 v85, v66
	v_mov_b32_e32 v86, v66
	v_mov_b32_e32 v87, v66
	v_mov_b32_e32 v106, v66
	v_mov_b32_e32 v107, v66
	s_waitcnt vmcnt(0)
	buffer_inv sc1
	s_waitcnt vmcnt(0)
	s_barrier
